# g1 solve update: strided operand reads of each MFMA issued together
# speedup vs baseline: 1.0075x; 1.0036x over previous
; #define LAS __attribute__((address_space(3)))
; __device__ __forceinline__ unsigned pk2(float lo, float hi) { const f32x2_ v = {lo, hi}; return __builtin_bit_cast(unsigned, __builtin_convertvector(v, bf16x2_)); }
; __device__ __forceinline__ f32x4 mfma16(bf16x8 a, bf16x8 b, f32x4 c) { return __builtin_amdgcn_mfma_f32_16x16x32_bf16(a, b, c, 0, 0, 0); }
; __device__ __forceinline__ void g1_phase(const PP P, int l, LAS unsigned char* lds) {
;     ...
;             if (act && R > 0 && 16 * R < L) {
;                 const int wv = gt >> 6, ln = gt & 63, fr = ln & 15, fq = ln >> 4, nkk = (16 * R + 31) >> 5;
;                 bf16x8 af[2];
; #pragma unroll
;                 for (int kk = 0; kk < 2; ++kk) { u32x4 w = {0u, 0u, 0u, 0u};
;                     if (kk < nkk && 32 * kk + fq * 8 < 16 * R) { const LAS float* pa = As + (16 * R + fr) * 64 + 32 * kk + fq * 8; const f32x4 a0 = *(const LAS f32x4*)pa, a1 = *(const LAS f32x4*)(pa + 4);
;                         w.x = pk2(a0[0], a0[1]); w.y = pk2(a0[2], a0[3]); w.z = pk2(a1[0], a1[1]); w.w = pk2(a1[2], a1[3]); }
;                     af[kk] = __builtin_bit_cast(bf16x8, w); }
; #pragma unroll
;                 for (int t = 0; t < 2; ++t) { const int nt = 2 * wv + t; LAS float* xb = ((nt < 4) ? ks : vs) + 16 * (nt & 3) + fr;
;                     f32x4 acc = {0.f, 0.f, 0.f, 0.f};
; #pragma unroll
;                     for (int kk = 0; kk < 2; ++kk) if (kk < nkk) { const LAS float* pb = xb + (32 * kk + fq * 8) * 65;
;                         u32x4 w; w.x = pk2(pb[0], pb[65]); w.y = pk2(pb[130], pb[195]); w.z = pk2(pb[260], pb[325]); w.w = pk2(pb[390], pb[455]);
;                         acc = mfma16(af[kk], __builtin_bit_cast(bf16x8, w), acc); }
; #pragma unroll
;                     for (int j = 0; j < 4; ++j) xb[(16 * R + fq * 4 + j) * 65] -= acc[j]; }
.LBB0_613:
	s_or_b64 exec, exec, s[28:29]
	ds_read2_b32 v[8:9], v106 offset1:65
	ds_read2_b32 v[10:11], v106 offset0:130 offset1:195
	v_add_u32_e32 v20, 0x400, v106
	ds_read2_b32 v[18:19], v20 offset0:134 offset1:199
	s_andn2_b64 vcc, exec, s[94:95]
	s_waitcnt lgkmcnt(2)
	v_cvt_pk_bf16_f32 v8, v8, v9
	s_waitcnt lgkmcnt(1)
	v_cvt_pk_bf16_f32 v9, v10, v11
	ds_read2_b32 v[10:11], v20 offset0:4 offset1:69
	s_waitcnt lgkmcnt(0)
	v_cvt_pk_bf16_f32 v10, v10, v11
	v_cvt_pk_bf16_f32 v11, v18, v19
	v_cndmask_b32_e64 v18, 0, 1, s[94:95]
	v_cmp_ne_u32_e64 s[78:79], 1, v18
	v_mfma_f32_16x16x32_bf16 v[8:11], v[4:7], v[8:11], 0
	v_add_u32_e32 v19, 0x2000, v106
	v_add_u32_e32 v18, 0x2400, v106
	s_cbranch_vccnz .LBB0_615
	ds_read2_b32 v[222:223], v19 offset0:32 offset1:97
	ds_read2_b32 v[224:225], v19 offset0:162 offset1:227
	ds_read2_b32 v[226:227], v18 offset0:36 offset1:101
	ds_read2_b32 v[228:229], v18 offset0:166 offset1:231
	s_waitcnt lgkmcnt(0)
	v_cvt_pk_bf16_f32 v70, v222, v223
	v_cvt_pk_bf16_f32 v71, v224, v225
	v_cvt_pk_bf16_f32 v72, v226, v227
	v_cvt_pk_bf16_f32 v73, v228, v229
	s_nop 1
	v_mfma_f32_16x16x32_bf16 v[8:11], v[0:3], v[70:73], v[8:11]
.LBB0_615:
	v_add_u32_e32 v37, s69, v103
	v_add_u32_e32 v21, 0x4000, v37
	ds_read2_b32 v[22:23], v21 offset0:64 offset1:129
	s_and_b64 vcc, exec, s[78:79]
	s_waitcnt lgkmcnt(0)
	s_nop 2
	v_sub_f32_e32 v8, v22, v8
	v_sub_f32_e32 v9, v23, v9
	ds_write2_b32 v21, v8, v9 offset0:64 offset1:129
	v_add_u32_e32 v8, 0x4200, v37
	ds_read2_b32 v[22:23], v8 offset0:66 offset1:131
	s_waitcnt lgkmcnt(0)
	v_sub_f32_e32 v9, v22, v10
	v_sub_f32_e32 v10, v23, v11
	ds_write2_b32 v8, v9, v10 offset0:66 offset1:131
	ds_read2_b32 v[222:223], v106 offset0:16 offset1:81
	ds_read2_b32 v[224:225], v106 offset0:146 offset1:211
	ds_read2_b32 v[226:227], v20 offset0:20 offset1:85
	ds_read2_b32 v[228:229], v20 offset0:150 offset1:215
	s_waitcnt lgkmcnt(0)
	v_cvt_pk_bf16_f32 v70, v222, v223
	v_cvt_pk_bf16_f32 v71, v224, v225
	v_cvt_pk_bf16_f32 v72, v226, v227
	v_cvt_pk_bf16_f32 v73, v228, v229
	s_nop 1
	v_mfma_f32_16x16x32_bf16 v[4:7], v[4:7], v[70:73], 0
	s_cbranch_vccnz .LBB0_617
	ds_read2_b32 v[222:223], v19 offset0:48 offset1:113
	ds_read2_b32 v[224:225], v19 offset0:178 offset1:243
	ds_read2_b32 v[226:227], v18 offset0:52 offset1:117
	ds_read2_b32 v[228:229], v18 offset0:182 offset1:247
	s_waitcnt lgkmcnt(0)
	v_cvt_pk_bf16_f32 v70, v222, v223
	v_cvt_pk_bf16_f32 v71, v224, v225
	v_cvt_pk_bf16_f32 v72, v226, v227
	v_cvt_pk_bf16_f32 v73, v228, v229
	s_nop 1
	v_mfma_f32_16x16x32_bf16 v[4:7], v[0:3], v[70:73], v[4:7]
